# stack5: stack3 + sliding-window loop issues cache-prefetch loads one tile further ahead (counted vmcnt keeps them in flight)
# speedup vs baseline: 1.0017x; 1.0017x over previous
; #define LAS __attribute__((address_space(3)))
; #define GAS __attribute__((address_space(1)))
; template <int KRS, bool HAS_X>
; __device__ __forceinline__ void tile_load(TileRegs<KRS, HAS_X>& R, const TileSrc& s, int t, int tid) {
;     const GAS bf16_t* kp = s.K + (size_t)t * 64 * 128 + tid * 8;
;     R.k0 = *(const GAS u32x4*)kp; R.k1 = *(const GAS u32x4*)(kp + 4096);
;     if (HAS_X) R.kx = *(const GAS u32x4*)(s.KX + (size_t)t * 64 * 64 + tid * 8);
;     const int d = tid >> 3, ch = tid & 7;
;     const GAS bf16_t* vp = s.VT + (size_t)d * s.ldv + t * 64 + ch * 8;
;     R.v0 = *(const GAS u32x4*)vp; R.v1 = *(const GAS u32x4*)(vp + (size_t)64 * s.ldv);
; }
; template <int KRS, bool HAS_X>
; __device__ __forceinline__ void tile_store(const TileRegs<KRS, HAS_X>& R, LAS unsigned char* buf, int tid) {
;     { const int row = tid >> 4, col = tid & 15; *(LAS u32x4*)(buf + row * KRS + col * 16) = R.k0; *(LAS u32x4*)(buf + (row + 32) * KRS + col * 16) = R.k1; }
;     if (HAS_X) { const int row = tid >> 3, col = tid & 7; *(LAS u32x4*)(buf + row * KRS + 256 + col * 16) = R.kx; }
;     { const int d = tid >> 3, ch = tid & 7; LAS unsigned char* vb = buf + 64 * KRS + d * VRS + ch * 16;
;       *(LAS u32x4*)(vb) = R.v0; *(LAS u32x4*)(vb + 64 * VRS) = R.v1; }
; template <int KRS, bool HAS_X, bool MIDSTORE, class Pre, class Body>
; __device__ __forceinline__ void flash_loop_pre(LAS unsigned char* lds, const TileSrc& src, int tb, int te, int tid, Pre&& pre, Body&& body) {
;     ...
;     for (int t = tb; t < te; ++t) {
;         const int cur = (t - tb) & 1;
;         if (t + 1 < te) tile_store<KRS, HAS_X>(R, lds + (cur ^ 1) * BUFB, tid);
;         if (t + 2 < te) tile_load<KRS, HAS_X>(R, src, t + 2, tid);
;         body(t, (const LAS unsigned char*)(lds + cur * BUFB), []() __attribute__((always_inline)) {});
.LBB0_1474:
	s_add_i32 s7, s8, s9
	s_add_i32 s6, s9, -8
	s_add_i32 s10, s7, -8
	s_and_b32 s6, s6, 1
	s_cmp_ge_i32 s10, s97
	s_cbranch_scc1 .LBB0_1476
	s_xor_b32 s10, s6, 1
	s_mul_i32 s10, s10, 0x8c00
	s_add_i32 s10, s10, 0
	v_add3_u32 v0, s10, v169, v175
	v_add3_u32 v2, s10, v174, v168
	s_waitcnt vmcnt(7)
	ds_write_b128 v0, v[144:147]
	s_waitcnt vmcnt(6)
	ds_write_b128 v0, v[148:151] offset:8704
	s_waitcnt vmcnt(5)
	ds_write_b128 v2, v[152:155] offset:17408
	s_waitcnt vmcnt(4)
	ds_write_b128 v2, v[156:159] offset:26624
.LBB0_1476:
	s_add_i32 s7, s7, -6
	s_cmp_gt_i32 s7, s97
	s_cbranch_scc1 .LBB0_1478
	v_add_co_u32_e32 v2, vcc, 0xffffe000, v172
	s_add_i32 s10, s12, 0xfffffe80
	s_nop 0
	v_addc_co_u32_e32 v3, vcc, -1, v173, vcc
	s_ashr_i32 s11, s10, 31
	global_load_dwordx4 v[144:147], v[2:3], off
	global_load_dwordx4 v[148:151], v[172:173], off
	v_lshl_add_u64 v[2:3], s[10:11], 1, v[170:171]
	v_add_co_u32_e32 v4, vcc, 0x200000, v2
	s_nop 1
	v_addc_co_u32_e32 v5, vcc, 0, v3, vcc
	global_load_dwordx4 v[152:155], v[2:3], off
	global_load_dwordx4 v[156:159], v[4:5], off
	global_load_dword v230, v[2:3], off offset:128
	global_load_dword v230, v[4:5], off offset:128
	v_add_co_u32_e32 v232, vcc, 0x2000, v172
	s_nop 1
	v_addc_co_u32_e32 v233, vcc, 0, v173, vcc
	global_load_dword v230, v[232:233], off
	v_add_co_u32_e32 v232, vcc, 0x4000, v172
	s_nop 1
	v_addc_co_u32_e32 v233, vcc, 0, v173, vcc
	global_load_dword v230, v[232:233], off
